# out-projection k-loop rescheduled like the in-projection loop: SGPR bases + 32-bit lane offsets replace the per-k-step 64-bit address VALU, fragment reads done by pair 10, LDS stores behind pairs 10-1
# speedup vs baseline: 1.0184x; 1.0029x over previous
; template <bool SWAP, bool SSQ, class AF>
; DI void gemm_main(AF asrc, int m0, const u16* __restrict__ Bw, int ldb, int K, char* smem,
;                   f32x16 (&acc)[4][2], float ssq_eps, float (&rs)[4]) {
;     ...
;   auto gload = [&](int kt) {
;     ASrc s = asrc(kt);
;     const unsigned voffA = (unsigned)(srow * (int)s.ld * 2 + skc * 16);
;     const char* ua = (const char*)s.p + (long)m0 * s.ld * 2;
; #pragma unroll
;     for (int i = 0; i < 8; ++i) ra[i] = *(const u32x4*)(ua + (long)(32 * i) * s.ld * 2 + voffA);
;     const char* ub = (const char*)Bw + (long)kt * 128;
; #pragma unroll
;     for (int i = 0; i < 4; ++i) rb[i] = *(const u32x4*)(ub + (long)(32 * i) * ldb * 2 + voffB);
;   };
;   auto sstore = [&]() {
; #pragma unroll
;     for (int i = 0; i < 8; ++i) *(u32x4*)(sA + lds_st + i * (32 * 144)) = ra[i];
; #pragma unroll
;     for (int i = 0; i < 4; ++i) *(u32x4*)(sB + lds_st + i * (32 * 144)) = rb[i];
;   };
;   const int nkt = K >> 6;
;   const char* pA = sA + (wm * 128 + lr) * 144 + lh * 16;
;   const char* pB = sB + (wn * 64 + lr) * 144 + lh * 16;
;   gload(0);
;   sstore();
;   __syncthreads();
; DI void phase_outproj(const Params& p, const GroupP& g, int l, char* smem, int vb) {
;     ...
;   for (int it = vb; it < ((ntiles + 7) & ~7); it += gridDim.x) {
;     const int tt = xcd_tile(it, ntiles);
;     if (tt < 0) continue;
;     int nt, mt;
;     tile_mn(tt, nmt, 16, mt, nt);
;     int m0 = mt * 256, n0 = nt * 128;
.LBB0_906:
	s_lshr_b32 s7, s6, 4
	s_and_b32 s7, s7, 0x7fffffc
	s_sub_i32 s8, s30, s7
	s_min_i32 s8, s8, 4
	s_abs_i32 s9, s8
	v_cvt_f32_u32_e32 v0, s9
	s_sub_i32 s11, 0, s9
	s_and_b32 s6, s6, 63
	s_ashr_i32 s10, s8, 31
	v_rcp_iflag_f32_e32 v0, v0
	v_readlane_b32 s16, v254, 36
	v_mov_b32_e32 v50, v200
	v_readlane_b32 s17, v254, 37
	v_mul_f32_e32 v0, 0x4f7ffffe, v0
	v_cvt_u32_f32_e32 v0, v0
	s_load_dwordx16 s[44:59], s[16:17], 0xb8
	v_readfirstlane_b32 s22, v50
	v_readfirstlane_b32 s12, v0
	s_mul_i32 s11, s11, s12
	s_mul_hi_u32 s11, s12, s11
	s_add_i32 s12, s12, s11
	s_mul_hi_u32 s11, s6, s12
	s_mul_i32 s12, s11, s9
	s_sub_i32 s12, s6, s12
	s_add_i32 s13, s11, 1
	s_sub_i32 s14, s12, s9
	s_cmp_ge_u32 s12, s9
	s_cselect_b32 s11, s13, s11
	s_cselect_b32 s12, s14, s12
	s_add_i32 s13, s11, 1
	s_cmp_ge_u32 s12, s9
	s_cselect_b32 s9, s13, s11
	s_add_i32 s7, s7, s6
	s_xor_b32 s6, s9, s10
	s_sub_i32 s6, s6, s10
	s_mul_i32 s8, s6, s8
	s_lshl_b32 s6, s6, 7
	s_sub_i32 s8, s7, s8
	s_ashr_i32 s7, s6, 31
	s_lshl_b32 s8, s8, 8
	s_lshl_b64 s[12:13], s[6:7], 12
	s_add_u32 s10, s26, s12
	s_addc_u32 s11, s27, s13
	s_ashr_i32 s9, s8, 31
	v_lshlrev_b32_e32 v0, 4, v50
	s_and_b32 s23, s22, 0xfffff80
	s_lshl_b64 s[14:15], s[8:9], 10
	v_ashrrev_i32_e32 v51, 3, v50
	s_waitcnt vmcnt(0)
	v_and_b32_e32 v132, 0x70, v0
	s_waitcnt lgkmcnt(0)
	s_add_u32 s14, s46, s14
	v_lshl_or_b32 v184, v51, 10, v132
	s_addc_u32 s15, s47, s15
	v_lshl_add_u64 v[28:29], s[14:15], 0, v[184:185]
	s_mov_b32 s7, 0x8000
	v_add_co_u32_e32 v4, vcc, s7, v28
	s_mov_b32 s7, 0x10000
	s_nop 0
	v_addc_co_u32_e32 v5, vcc, 0, v29, vcc
	v_add_co_u32_e32 v8, vcc, s7, v28
	s_mov_b32 s7, 0x18000
	s_nop 0
	v_addc_co_u32_e32 v9, vcc, 0, v29, vcc
	v_add_co_u32_e32 v12, vcc, s7, v28
	s_mov_b32 s7, 0x30000
	s_nop 0
	v_addc_co_u32_e32 v13, vcc, 0, v29, vcc
	v_add_co_u32_e32 v16, vcc, s75, v28
	v_lshl_or_b32 v48, v51, 12, v132
	s_nop 0
	v_addc_co_u32_e32 v17, vcc, 0, v29, vcc
	v_add_co_u32_e32 v20, vcc, s65, v28
	v_mov_b32_e32 v49, v185
	s_nop 0
	v_addc_co_u32_e32 v21, vcc, 0, v29, vcc
	v_add_co_u32_e32 v24, vcc, s7, v28
	s_mov_b32 s7, 0x38000
	s_nop 0
	v_addc_co_u32_e32 v25, vcc, 0, v29, vcc
	v_add_co_u32_e32 v28, vcc, s7, v28
	v_lshl_add_u64 v[44:45], s[10:11], 0, v[48:49]
	s_nop 0
	v_addc_co_u32_e32 v29, vcc, 0, v29, vcc
	v_add_co_u32_e32 v36, vcc, s75, v44
	s_mov_b32 s7, 0x40000
	s_nop 0
	v_addc_co_u32_e32 v37, vcc, 0, v45, vcc
	v_add_co_u32_e32 v40, vcc, s7, v44
	global_load_dwordx4 v[0:3], v184, s[14:15]
	s_nop 0
	v_addc_co_u32_e32 v41, vcc, 0, v45, vcc
	global_load_dwordx4 v[4:7], v[4:5], off
	s_nop 0
	global_load_dwordx4 v[8:11], v[8:9], off
	s_nop 0
	global_load_dwordx4 v[12:15], v[12:13], off
	s_nop 0
	global_load_dwordx4 v[16:19], v[16:17], off
	s_nop 0
	global_load_dwordx4 v[20:23], v[20:21], off
	s_nop 0
	global_load_dwordx4 v[24:27], v[24:25], off
	s_mov_b32 s7, 0x60000
	global_load_dwordx4 v[28:31], v[28:29], off
	v_add_co_u32_e32 v44, vcc, s7, v44
	global_load_dwordx4 v[32:35], v48, s[10:11]
	s_nop 0
	global_load_dwordx4 v[36:39], v[36:37], off
	s_nop 0
	global_load_dwordx4 v[40:43], v[40:41], off
	v_addc_co_u32_e32 v45, vcc, 0, v45, vcc
	global_load_dwordx4 v[44:47], v[44:45], off
	v_mad_u64_u32 v[134:135], s[10:11], v51, s64, v[132:133]
	v_and_b32_e32 v52, 31, v50
	s_lshl_b64 s[10:11], s[8:9], 1
	v_lshrrev_b32_e32 v50, 1, v50
	v_and_or_b32 v53, s22, 64, v52
	v_or_b32_e32 v52, s23, v52
	s_add_u32 s12, s37, s12
	v_and_b32_e32 v50, 16, v50
	v_mul_u32_u24_e32 v53, 0x90, v53
	v_mul_lo_u32 v52, v52, s64
	s_addc_u32 s13, s38, s13
	s_mov_b32 s42, 0
	s_mov_b32 s7, 64
	v_lshlrev_b32_e32 v139, 1, v51
	v_lshl_add_u64 v[136:137], s[12:13], 0, v[48:49]
	s_mov_b64 s[12:13], 0
	v_add_u32_e32 v133, v52, v50
	v_add_u32_e32 v135, v53, v50
	s_waitcnt vmcnt(11)
	ds_write_b128 v134, v[0:3]
	s_waitcnt vmcnt(10)
	ds_write_b128 v134, v[4:7] offset:4608
	s_waitcnt vmcnt(9)
	ds_write_b128 v134, v[8:11] offset:9216
	s_waitcnt vmcnt(8)
	ds_write_b128 v134, v[12:15] offset:13824
	s_waitcnt vmcnt(7)
	ds_write_b128 v134, v[16:19] offset:18432
	s_waitcnt vmcnt(6)
	ds_write_b128 v134, v[20:23] offset:23040
	s_waitcnt vmcnt(5)
	ds_write_b128 v134, v[24:27] offset:27648
	s_waitcnt vmcnt(4)
	ds_write_b128 v134, v[28:31] offset:32256
	s_waitcnt vmcnt(3)
	ds_write_b128 v134, v[32:35] offset:36864
	s_waitcnt vmcnt(2)
	ds_write_b128 v134, v[36:39] offset:41472
	s_waitcnt vmcnt(1)
	ds_write_b128 v134, v[40:43] offset:46080
	s_waitcnt vmcnt(0)
; template <bool SWAP, bool SSQ, class AF>
; DI void gemm_main(AF asrc, int m0, const u16* __restrict__ Bw, int ldb, int K, char* smem,
;                   f32x16 (&acc)[4][2], float ssq_eps, float (&rs)[4]) {
;     ...
;   for (int mi = 0; mi < 4; ++mi)
; #pragma unroll
;     for (int ni = 0; ni < 2; ++ni)
; #pragma unroll
;       for (int i = 0; i < 16; ++i) acc[mi][ni][i] = 0.f;
;   auto gload = [&](int kt) {
;     ASrc s = asrc(kt);
;     const unsigned voffA = (unsigned)(srow * (int)s.ld * 2 + skc * 16);
;     const char* ua = (const char*)s.p + (long)m0 * s.ld * 2;
; #pragma unroll
;     for (int i = 0; i < 8; ++i) ra[i] = *(const u32x4*)(ua + (long)(32 * i) * s.ld * 2 + voffA);
;     const char* ub = (const char*)Bw + (long)kt * 128;
; #pragma unroll
;     for (int i = 0; i < 4; ++i) rb[i] = *(const u32x4*)(ub + (long)(32 * i) * ldb * 2 + voffB);
;   };
;   auto sstore = [&]() {
; #pragma unroll
;     for (int i = 0; i < 8; ++i) *(u32x4*)(sA + lds_st + i * (32 * 144)) = ra[i];
; #pragma unroll
;     for (int i = 0; i < 4; ++i) *(u32x4*)(sB + lds_st + i * (32 * 144)) = rb[i];
;   };
;   const int nkt = K >> 6;
;   const char* pA = sA + (wm * 128 + lr) * 144 + lh * 16;
;   const char* pB = sB + (wn * 64 + lr) * 144 + lh * 16;
;   gload(0);
;   sstore();
;   __syncthreads();
;   for (int kt = 0; kt < nkt; ++kt) {
;     if (kt + 1 < nkt) gload(kt + 1);
;     __builtin_amdgcn_sched_barrier(0);
;     {
;       bf16x8 ar[3], br[2][2];
;       ar[0] = *(const bf16x8*)(pA);
;       ar[1] = *(const bf16x8*)(pA + 32 * 144);
	ds_write_b128 v134, v[44:47] offset:50688
	v_mov_b32_e32 v0, 0
	v_mov_b32_e32 v1, v0
	v_mov_b32_e32 v2, v0
	v_mov_b32_e32 v3, v0
	v_mov_b32_e32 v4, v0
	v_mov_b32_e32 v5, v0
	v_mov_b32_e32 v6, v0
	v_mov_b32_e32 v7, v0
	v_mov_b32_e32 v8, v0
	v_mov_b32_e32 v9, v0
	v_mov_b32_e32 v10, v0
	v_mov_b32_e32 v11, v0
	v_mov_b32_e32 v12, v0
	v_mov_b32_e32 v13, v0
	v_mov_b32_e32 v14, v0
	v_mov_b32_e32 v15, v0
	v_mov_b32_e32 v16, v0
	v_mov_b32_e32 v17, v0
	v_mov_b32_e32 v18, v0
	v_mov_b32_e32 v19, v0
	v_mov_b32_e32 v20, v0
	v_mov_b32_e32 v21, v0
	v_mov_b32_e32 v22, v0
	v_mov_b32_e32 v23, v0
	v_mov_b32_e32 v24, v0
	v_mov_b32_e32 v25, v0
	v_mov_b32_e32 v26, v0
	v_mov_b32_e32 v27, v0
	v_mov_b32_e32 v28, v0
	v_mov_b32_e32 v29, v0
	v_mov_b32_e32 v30, v0
	v_mov_b32_e32 v31, v0
	v_mov_b32_e32 v32, v0
	v_mov_b32_e32 v33, v0
	v_mov_b32_e32 v34, v0
	v_mov_b32_e32 v35, v0
	v_mov_b32_e32 v36, v0
	v_mov_b32_e32 v37, v0
	v_mov_b32_e32 v38, v0
	v_mov_b32_e32 v39, v0
	v_mov_b32_e32 v40, v0
	v_mov_b32_e32 v41, v0
	v_mov_b32_e32 v42, v0
	v_mov_b32_e32 v43, v0
	v_mov_b32_e32 v44, v0
	v_mov_b32_e32 v45, v0
	v_mov_b32_e32 v46, v0
	v_mov_b32_e32 v47, v0
	v_mov_b32_e32 v48, v0
	v_mov_b32_e32 v49, v0
	v_mov_b32_e32 v50, v0
	v_mov_b32_e32 v51, v0
	v_mov_b32_e32 v52, v0
	v_mov_b32_e32 v53, v0
	v_mov_b32_e32 v54, v0
	v_mov_b32_e32 v55, v0
	v_mov_b32_e32 v56, v0
	v_mov_b32_e32 v57, v0
	v_mov_b32_e32 v58, v0
	v_mov_b32_e32 v59, v0
	v_mov_b32_e32 v60, v0
	v_mov_b32_e32 v61, v0
	v_mov_b32_e32 v62, v0
	v_mov_b32_e32 v63, v0
	v_mov_b32_e32 v64, v0
	v_mov_b32_e32 v65, v0
	v_mov_b32_e32 v66, v0
	v_mov_b32_e32 v67, v0
	v_mov_b32_e32 v68, v0
	v_mov_b32_e32 v69, v0
	v_mov_b32_e32 v70, v0
	v_mov_b32_e32 v71, v0
	v_mov_b32_e32 v72, v0
	v_mov_b32_e32 v73, v0
	v_mov_b32_e32 v74, v0
	v_mov_b32_e32 v75, v0
	v_mov_b32_e32 v76, v0
	v_mov_b32_e32 v77, v0
	v_mov_b32_e32 v78, v0
	v_mov_b32_e32 v79, v0
	v_mov_b32_e32 v80, v0
	v_mov_b32_e32 v81, v0
	v_mov_b32_e32 v82, v0
	v_mov_b32_e32 v83, v0
	v_mov_b32_e32 v84, v0
	v_mov_b32_e32 v85, v0
	v_mov_b32_e32 v86, v0
	v_mov_b32_e32 v87, v0
	v_mov_b32_e32 v88, v0
	v_mov_b32_e32 v89, v0
	v_mov_b32_e32 v90, v0
	v_mov_b32_e32 v91, v0
	v_mov_b32_e32 v92, v0
	v_mov_b32_e32 v93, v0
	v_mov_b32_e32 v94, v0
	v_mov_b32_e32 v95, v0
	v_mov_b32_e32 v96, v0
	v_mov_b32_e32 v97, v0
	v_mov_b32_e32 v98, v0
	v_mov_b32_e32 v99, v0
	v_mov_b32_e32 v100, v0
	v_mov_b32_e32 v101, v0
	v_mov_b32_e32 v102, v0
	v_mov_b32_e32 v103, v0
	v_mov_b32_e32 v104, v0
	v_mov_b32_e32 v105, v0
	v_mov_b32_e32 v106, v0
	v_mov_b32_e32 v107, v0
	v_mov_b32_e32 v108, v0
	v_mov_b32_e32 v109, v0
	v_mov_b32_e32 v110, v0
	v_mov_b32_e32 v111, v0
	v_mov_b32_e32 v112, v0
	v_mov_b32_e32 v113, v0
	v_mov_b32_e32 v114, v0
	v_mov_b32_e32 v115, v0
	v_mov_b32_e32 v116, v0
	v_mov_b32_e32 v117, v0
	v_mov_b32_e32 v118, v0
	v_mov_b32_e32 v119, v0
	v_mov_b32_e32 v120, v0
	v_mov_b32_e32 v121, v0
	v_mov_b32_e32 v122, v0
	v_mov_b32_e32 v123, v0
	v_mov_b32_e32 v124, v0
	v_mov_b32_e32 v125, v0
	v_mov_b32_e32 v126, v0
	v_mov_b32_e32 v127, v0
	v_readlane_b32 s16, v254, 36
	v_readlane_b32 s17, v254, 37
	s_nop 0
	s_load_dwordx2 s[54:55], s[16:17], 0xe0
	s_load_dwordx2 s[46:47], s[16:17], 0x100
	s_waitcnt lgkmcnt(0)
	s_barrier
	v_readfirstlane_b32 s52, v136
	v_readfirstlane_b32 s53, v137
	s_nop 1
	v_subrev_u32_e32 v245, s52, v136
	s_add_u32 s52, s52, 0x80
	s_addc_u32 s53, s53, 0
	v_add_u32_e32 v246, s75, v245
	v_add_u32_e32 v247, 0x40000, v245
	v_add_u32_e32 v248, 0x60000, v245
	ds_read_b128 v[190:193], v135 offset:36864
	ds_read_b128 v[194:197], v135 offset:41472
	ds_read_b128 v[202:205], v133
	ds_read_b128 v[206:209], v133 offset:4608
	ds_read_b128 v[218:221], v133 offset:9216
	s_branch .LBB0_908
; #define MFMA(a, b, c) __builtin_amdgcn_mfma_f32_32x32x16_bf16((a), (b), (c), 0, 0, 0)
; template <bool SWAP, bool SSQ, class AF>
; DI void gemm_main(AF asrc, int m0, const u16* __restrict__ Bw, int ldb, int K, char* smem,
;                   f32x16 (&acc)[4][2], float ssq_eps, float (&rs)[4]) {
;     ...
;   for (int kt = 0; kt < nkt; ++kt) {
;     if (kt + 1 < nkt) gload(kt + 1);
;     __builtin_amdgcn_sched_barrier(0);
;     {
;       bf16x8 ar[3], br[2][2];
;       ar[0] = *(const bf16x8*)(pA);
;       ar[1] = *(const bf16x8*)(pA + 32 * 144);
;       br[0][0] = *(const bf16x8*)(pB);
;       br[0][1] = *(const bf16x8*)(pB + 32 * 144);
;       __builtin_amdgcn_sched_group_barrier(0x100, 4, 0);
; #pragma unroll
;       for (int t = 0; t < 16; ++t) {
;         const int ks = t >> 2, mi = t & 3;
;         if (t + 2 < 16) {
;           ar[(t + 2) % 3] = *(const bf16x8*)(pA + ((t + 2) & 3) * (32 * 144) + ((t + 2) >> 2) * 32);
;           if (mi == 1 && ks + 1 < 4) {
;             br[(ks + 1) & 1][0] = *(const bf16x8*)(pB + (ks + 1) * 32);
;             br[(ks + 1) & 1][1] = *(const bf16x8*)(pB + 32 * 144 + (ks + 1) * 32);
;             __builtin_amdgcn_sched_group_barrier(0x100, 3, 0);
;           } else {
;             __builtin_amdgcn_sched_group_barrier(0x100, 1, 0);
;           }
;         }
;         acc[mi][0] = SWAP ? MFMA(br[ks & 1][0], ar[t % 3], acc[mi][0]) : MFMA(ar[t % 3], br[ks & 1][0], acc[mi][0]);
;         acc[mi][1] = SWAP ? MFMA(br[ks & 1][1], ar[t % 3], acc[mi][1]) : MFMA(ar[t % 3], br[ks & 1][1], acc[mi][1]);
;         __builtin_amdgcn_sched_group_barrier(0x008, 2, 0);
;         if (SSQ) {
;           u32x4 u = __builtin_bit_cast(u32x4, ar[t % 3]);
; #pragma unroll
;           for (int j = 0; j < 4; ++j) rs[mi] = dot2bf(u[j], rs[mi]);
;         }
;       }
;     }
;     __syncthreads();
;     if (kt + 1 < nkt) sstore();
;     __syncthreads();
;   }
; DI void phase_outproj(const Params& p, const GroupP& g, int l, char* smem, int vb) {
;     ...
;         [&](int kt) {
;           int k0 = kt * 64;
;           if (k0 < 512) return ASrc{uf + k0, 512};
;           if (k0 < 1536) { int kk = k0 - 512; return ASrc{q + (kk >> 7) * 192 + (kk & 127), 1536}; }
;           return ASrc{qd + (k0 - 1536), 512};
;         },
.LBB0_907:
	s_mul_i32 s24, s10, s23
	s_mul_hi_u32 s25, s10, s22
	s_add_i32 s24, s25, s24
	s_mul_i32 s25, s11, s22
	s_add_i32 s24, s24, s25
	s_mul_i32 s25, s10, s22
	v_mul_lo_u32 v140, v139, s22
	s_add_u32 s14, s14, s25
	v_or_b32_e32 v184, v140, v132
	s_addc_u32 s15, s15, s24
	s_lshl_b64 s[50:51], s[22:23], 6
	s_lshl_b64 s[48:49], s[22:23], 8
	v_add_u32_e32 v242, s50, v184
	s_add_u32 s48, s14, s48
	v_add_u32_e32 v243, s50, v242
	s_addc_u32 s49, s15, s49
	v_add_u32_e32 v244, s50, v243
	ds_read_b128 v[222:225], v133 offset:13824
	global_load_dwordx4 v[140:143], v184, s[14:15]
	global_load_dwordx4 v[144:147], v242, s[14:15]
	s_waitcnt lgkmcnt(3)
	v_mfma_f32_32x32x16_bf16 v[112:127], v[190:193], v[202:205], v[112:127]
	v_mfma_f32_32x32x16_bf16 v[96:111], v[194:197], v[202:205], v[96:111]
	ds_read_b128 v[202:205], v135 offset:36896
	ds_read_b128 v[226:229], v135 offset:41504
	global_load_dwordx4 v[148:151], v243, s[14:15]
	global_load_dwordx4 v[152:155], v244, s[14:15]
	s_waitcnt lgkmcnt(4)
	v_mfma_f32_32x32x16_bf16 v[80:95], v[190:193], v[206:209], v[80:95]
	v_mfma_f32_32x32x16_bf16 v[64:79], v[194:197], v[206:209], v[64:79]
	ds_read_b128 v[206:209], v133 offset:32
	global_load_dwordx4 v[156:159], v184, s[48:49]
	global_load_dwordx4 v[160:163], v242, s[48:49]
	s_waitcnt lgkmcnt(4)
	v_mfma_f32_32x32x16_bf16 v[48:63], v[190:193], v[218:221], v[48:63]
	v_mfma_f32_32x32x16_bf16 v[32:47], v[194:197], v[218:221], v[32:47]
	ds_read_b128 v[218:221], v133 offset:4640
	global_load_dwordx4 v[164:167], v243, s[48:49]
	global_load_dwordx4 v[168:171], v244, s[48:49]
	s_waitcnt lgkmcnt(4)
	v_mfma_f32_32x32x16_bf16 v[16:31], v[190:193], v[222:225], v[16:31]
	v_mfma_f32_32x32x16_bf16 v[0:15], v[194:197], v[222:225], v[0:15]
	ds_read_b128 v[190:193], v133 offset:9248
	ds_read_b128 v[194:197], v133 offset:13856
	global_load_dwordx4 v[172:175], v245, s[52:53]
	global_load_dwordx4 v[176:179], v246, s[52:53]
	s_waitcnt lgkmcnt(3)
	v_mfma_f32_32x32x16_bf16 v[112:127], v[202:205], v[206:209], v[112:127]
	v_mfma_f32_32x32x16_bf16 v[96:111], v[226:229], v[206:209], v[96:111]
	ds_read_b128 v[206:209], v135 offset:36928
	ds_read_b128 v[230:233], v135 offset:41536
	global_load_dwordx4 v[180:183], v247, s[52:53]
	global_load_dwordx4 v[186:189], v248, s[52:53]
	s_waitcnt lgkmcnt(4)
	v_mfma_f32_32x32x16_bf16 v[80:95], v[202:205], v[218:221], v[80:95]
	v_mfma_f32_32x32x16_bf16 v[64:79], v[226:229], v[218:221], v[64:79]
	ds_read_b128 v[218:221], v133 offset:64
	ds_read_b128 v[234:237], v133 offset:4672
	s_waitcnt lgkmcnt(5)
	v_mfma_f32_32x32x16_bf16 v[48:63], v[202:205], v[190:193], v[48:63]
	v_mfma_f32_32x32x16_bf16 v[32:47], v[226:229], v[190:193], v[32:47]
	ds_read_b128 v[190:193], v133 offset:9280
	s_waitcnt lgkmcnt(5)
	v_mfma_f32_32x32x16_bf16 v[16:31], v[202:205], v[194:197], v[16:31]
	v_mfma_f32_32x32x16_bf16 v[0:15], v[226:229], v[194:197], v[0:15]
	ds_read_b128 v[202:205], v133 offset:13888
	ds_read_b128 v[238:241], v135 offset:36960
	ds_read_b128 v[222:225], v135 offset:41568
	s_waitcnt lgkmcnt(5)
	v_mfma_f32_32x32x16_bf16 v[112:127], v[206:209], v[218:221], v[112:127]
	v_mfma_f32_32x32x16_bf16 v[96:111], v[230:233], v[218:221], v[96:111]
	ds_read_b128 v[194:197], v133 offset:96
	ds_read_b128 v[218:221], v133 offset:4704
	s_waitcnt lgkmcnt(6)
	v_mfma_f32_32x32x16_bf16 v[80:95], v[206:209], v[234:237], v[80:95]
	v_mfma_f32_32x32x16_bf16 v[64:79], v[230:233], v[234:237], v[64:79]
	ds_read_b128 v[226:229], v133 offset:9312
	ds_read_b128 v[234:237], v133 offset:13920
	s_waitcnt lgkmcnt(0)
	s_barrier
	v_mfma_f32_32x32x16_bf16 v[48:63], v[206:209], v[190:193], v[48:63]
	v_mfma_f32_32x32x16_bf16 v[32:47], v[230:233], v[190:193], v[32:47]
	s_waitcnt vmcnt(11)
	ds_write_b128 v134, v[140:143]
	s_waitcnt vmcnt(10)
	ds_write_b128 v134, v[144:147] offset:4608
	s_waitcnt vmcnt(9)
	ds_write_b128 v134, v[148:151] offset:9216
	s_waitcnt vmcnt(8)
	ds_write_b128 v134, v[152:155] offset:13824
	v_mfma_f32_32x32x16_bf16 v[16:31], v[206:209], v[202:205], v[16:31]
	v_mfma_f32_32x32x16_bf16 v[0:15], v[230:233], v[202:205], v[0:15]
	s_waitcnt vmcnt(7)
	ds_write_b128 v134, v[156:159] offset:18432
	s_waitcnt vmcnt(6)
	ds_write_b128 v134, v[160:163] offset:23040
	s_waitcnt vmcnt(5)
	ds_write_b128 v134, v[164:167] offset:27648
	s_waitcnt vmcnt(4)
	ds_write_b128 v134, v[168:171] offset:32256
	v_mfma_f32_32x32x16_bf16 v[112:127], v[238:241], v[194:197], v[112:127]
	v_mfma_f32_32x32x16_bf16 v[96:111], v[222:225], v[194:197], v[96:111]
	s_waitcnt vmcnt(3)
	ds_write_b128 v134, v[172:175] offset:36864
	s_waitcnt vmcnt(2)
	ds_write_b128 v134, v[176:179] offset:41472
	s_waitcnt vmcnt(1)
	ds_write_b128 v134, v[180:183] offset:46080
	s_waitcnt vmcnt(0)
	ds_write_b128 v134, v[186:189] offset:50688
	v_mfma_f32_32x32x16_bf16 v[80:95], v[238:241], v[218:221], v[80:95]
	v_mfma_f32_32x32x16_bf16 v[64:79], v[222:225], v[218:221], v[64:79]
	s_waitcnt lgkmcnt(0)
	s_barrier
	ds_read_b128 v[190:193], v135 offset:36864
	ds_read_b128 v[194:197], v135 offset:41472
	ds_read_b128 v[202:205], v133
	ds_read_b128 v[206:209], v133 offset:4608
	ds_read_b128 v[218:221], v133 offset:9216
	v_mfma_f32_32x32x16_bf16 v[48:63], v[238:241], v[226:229], v[48:63]
	v_mfma_f32_32x32x16_bf16 v[32:47], v[222:225], v[226:229], v[32:47]
	v_mfma_f32_32x32x16_bf16 v[16:31], v[238:241], v[234:237], v[16:31]
	v_mfma_f32_32x32x16_bf16 v[0:15], v[222:225], v[234:237], v[0:15]
	s_add_u32 s52, s52, 0x80
	s_addc_u32 s53, s53, 0
	s_add_u32 s12, s12, 0x80
	s_addc_u32 s13, s13, 0
	s_add_i32 s7, s7, 64
	s_mov_b32 s42, s9
	s_cmpk_lg_i32 s12, 0xf80
	s_cbranch_scc0 .LBB0_916

; template <bool SWAP, bool SSQ, class AF>
; DI void gemm_main(AF asrc, int m0, const u16* __restrict__ Bw, int ldb, int K, char* smem,
;                   f32x16 (&acc)[4][2], float ssq_eps, float (&rs)[4]) {
;     ...
;   auto gload = [&](int kt) {
;     ASrc s = asrc(kt);
;     const unsigned voffA = (unsigned)(srow * (int)s.ld * 2 + skc * 16);
;     const char* ua = (const char*)s.p + (long)m0 * s.ld * 2;
; #pragma unroll
;     for (int i = 0; i < 8; ++i) ra[i] = *(const u32x4*)(ua + (long)(32 * i) * s.ld * 2 + voffA);
;     const char* ub = (const char*)Bw + (long)kt * 128;
; #pragma unroll
;     for (int i = 0; i < 4; ++i) rb[i] = *(const u32x4*)(ub + (long)(32 * i) * ldb * 2 + voffB);
;   };
;   auto sstore = [&]() {
; #pragma unroll
;     for (int i = 0; i < 8; ++i) *(u32x4*)(sA + lds_st + i * (32 * 144)) = ra[i];
; #pragma unroll
;     for (int i = 0; i < 4; ++i) *(u32x4*)(sB + lds_st + i * (32 * 144)) = rb[i];
;   };
;   const int nkt = K >> 6;
;   const char* pA = sA + (wm * 128 + lr) * 144 + lh * 16;
;   const char* pB = sB + (wn * 64 + lr) * 144 + lh * 16;
;   gload(0);
;   sstore();
;   __syncthreads();
; DI void phase_outproj(const Params& p, const GroupP& g, int l, char* smem, int vb) {
;     ...
;   for (int it = vb; it < ((ntiles + 7) & ~7); it += gridDim.x) {
;     const int tt = xcd_tile(it, ntiles);
;     if (tt < 0) continue;
;     int nt, mt;
;     tile_mn(tt, nmt, 16, mt, nt);
;     int m0 = mt * 256, n0 = nt * 128;
.LBB0_963:
	s_lshr_b32 s7, s6, 4
	s_and_b32 s7, s7, 0x7fffffc
	s_sub_i32 s8, s30, s7
	s_min_i32 s8, s8, 4
	s_abs_i32 s9, s8
	v_cvt_f32_u32_e32 v0, s9
	s_sub_i32 s11, 0, s9
	s_and_b32 s6, s6, 63
	s_ashr_i32 s10, s8, 31
	v_rcp_iflag_f32_e32 v0, v0
	v_readlane_b32 s16, v254, 36
	v_mov_b32_e32 v50, v200
	v_readlane_b32 s17, v254, 37
	v_mul_f32_e32 v0, 0x4f7ffffe, v0
	v_cvt_u32_f32_e32 v0, v0
	s_load_dwordx16 s[44:59], s[16:17], 0x28
	v_readfirstlane_b32 s22, v50
	v_readfirstlane_b32 s12, v0
	s_mul_i32 s11, s11, s12
	s_mul_hi_u32 s11, s12, s11
	s_add_i32 s12, s12, s11
	s_mul_hi_u32 s11, s6, s12
	s_mul_i32 s12, s11, s9
	s_sub_i32 s12, s6, s12
	s_add_i32 s13, s11, 1
	s_sub_i32 s14, s12, s9
	s_cmp_ge_u32 s12, s9
	s_cselect_b32 s11, s13, s11
	s_cselect_b32 s12, s14, s12
	s_add_i32 s13, s11, 1
	s_cmp_ge_u32 s12, s9
	s_cselect_b32 s9, s13, s11
	s_add_i32 s7, s7, s6
	s_xor_b32 s6, s9, s10
	s_sub_i32 s6, s6, s10
	s_mul_i32 s8, s6, s8
	s_lshl_b32 s6, s6, 7
	s_sub_i32 s8, s7, s8
	s_ashr_i32 s7, s6, 31
	s_lshl_b32 s8, s8, 8
	s_lshl_b64 s[12:13], s[6:7], 12
	s_add_u32 s10, s26, s12
	s_addc_u32 s11, s27, s13
	s_ashr_i32 s9, s8, 31
	v_lshlrev_b32_e32 v0, 4, v50
	s_and_b32 s23, s22, 0xfffff80
	s_lshl_b64 s[14:15], s[8:9], 10
	v_ashrrev_i32_e32 v51, 3, v50
	s_waitcnt vmcnt(0)
	v_and_b32_e32 v132, 0x70, v0
	s_waitcnt lgkmcnt(0)
	s_add_u32 s14, s46, s14
	v_lshl_or_b32 v184, v51, 10, v132
	s_addc_u32 s15, s47, s15
	v_lshl_add_u64 v[28:29], s[14:15], 0, v[184:185]
	s_mov_b32 s7, 0x8000
	v_add_co_u32_e32 v4, vcc, s7, v28
	s_mov_b32 s7, 0x10000
	s_nop 0
	v_addc_co_u32_e32 v5, vcc, 0, v29, vcc
	v_add_co_u32_e32 v8, vcc, s7, v28
	s_mov_b32 s7, 0x18000
	s_nop 0
	v_addc_co_u32_e32 v9, vcc, 0, v29, vcc
	v_add_co_u32_e32 v12, vcc, s7, v28
	s_mov_b32 s7, 0x30000
	s_nop 0
	v_addc_co_u32_e32 v13, vcc, 0, v29, vcc
	v_add_co_u32_e32 v16, vcc, s75, v28
	v_lshl_or_b32 v48, v51, 12, v132
	s_nop 0
	v_addc_co_u32_e32 v17, vcc, 0, v29, vcc
	v_add_co_u32_e32 v20, vcc, s65, v28
	v_mov_b32_e32 v49, v185
	s_nop 0
	v_addc_co_u32_e32 v21, vcc, 0, v29, vcc
	v_add_co_u32_e32 v24, vcc, s7, v28
	s_mov_b32 s7, 0x38000
	s_nop 0
	v_addc_co_u32_e32 v25, vcc, 0, v29, vcc
	v_add_co_u32_e32 v28, vcc, s7, v28
	v_lshl_add_u64 v[44:45], s[10:11], 0, v[48:49]
	s_nop 0
	v_addc_co_u32_e32 v29, vcc, 0, v29, vcc
	v_add_co_u32_e32 v36, vcc, s75, v44
	s_mov_b32 s7, 0x40000
	s_nop 0
	v_addc_co_u32_e32 v37, vcc, 0, v45, vcc
	v_add_co_u32_e32 v40, vcc, s7, v44
	global_load_dwordx4 v[0:3], v184, s[14:15]
	s_nop 0
	v_addc_co_u32_e32 v41, vcc, 0, v45, vcc
	global_load_dwordx4 v[4:7], v[4:5], off
	s_nop 0
	global_load_dwordx4 v[8:11], v[8:9], off
	s_nop 0
	global_load_dwordx4 v[12:15], v[12:13], off
	s_nop 0
	global_load_dwordx4 v[16:19], v[16:17], off
	s_nop 0
	global_load_dwordx4 v[20:23], v[20:21], off
	s_nop 0
	global_load_dwordx4 v[24:27], v[24:25], off
	s_mov_b32 s7, 0x60000
	global_load_dwordx4 v[28:31], v[28:29], off
	v_add_co_u32_e32 v44, vcc, s7, v44
	global_load_dwordx4 v[32:35], v48, s[10:11]
	s_nop 0
	global_load_dwordx4 v[36:39], v[36:37], off
	s_nop 0
	global_load_dwordx4 v[40:43], v[40:41], off
	v_addc_co_u32_e32 v45, vcc, 0, v45, vcc
	global_load_dwordx4 v[44:47], v[44:45], off
	v_mad_u64_u32 v[134:135], s[10:11], v51, s64, v[132:133]
	v_and_b32_e32 v52, 31, v50
	s_lshl_b64 s[10:11], s[8:9], 1
	v_lshrrev_b32_e32 v50, 1, v50
	v_and_or_b32 v53, s22, 64, v52
	v_or_b32_e32 v52, s23, v52
	s_add_u32 s12, s28, s12
	v_and_b32_e32 v50, 16, v50
	v_mul_u32_u24_e32 v53, 0x90, v53
	v_mul_lo_u32 v52, v52, s64
	s_addc_u32 s13, s38, s13
	s_mov_b32 s41, 0
	s_mov_b32 s7, 64
	v_lshlrev_b32_e32 v139, 1, v51
	v_lshl_add_u64 v[136:137], s[12:13], 0, v[48:49]
	s_mov_b64 s[12:13], 0
	v_add_u32_e32 v133, v52, v50
	v_add_u32_e32 v135, v53, v50
	s_waitcnt vmcnt(11)
	ds_write_b128 v134, v[0:3]
	s_waitcnt vmcnt(10)
	ds_write_b128 v134, v[4:7] offset:4608
	s_waitcnt vmcnt(9)
	ds_write_b128 v134, v[8:11] offset:9216
	s_waitcnt vmcnt(8)
	ds_write_b128 v134, v[12:15] offset:13824
	s_waitcnt vmcnt(7)
	ds_write_b128 v134, v[16:19] offset:18432
	s_waitcnt vmcnt(6)
	ds_write_b128 v134, v[20:23] offset:23040
	s_waitcnt vmcnt(5)
	ds_write_b128 v134, v[24:27] offset:27648
	s_waitcnt vmcnt(4)
	ds_write_b128 v134, v[28:31] offset:32256
	s_waitcnt vmcnt(3)
	ds_write_b128 v134, v[32:35] offset:36864
	s_waitcnt vmcnt(2)
	ds_write_b128 v134, v[36:39] offset:41472
	s_waitcnt vmcnt(1)
	ds_write_b128 v134, v[40:43] offset:46080
	s_waitcnt vmcnt(0)
; template <bool SWAP, bool SSQ, class AF>
; DI void gemm_main(AF asrc, int m0, const u16* __restrict__ Bw, int ldb, int K, char* smem,
;                   f32x16 (&acc)[4][2], float ssq_eps, float (&rs)[4]) {
;     ...
;   for (int mi = 0; mi < 4; ++mi)
; #pragma unroll
;     for (int ni = 0; ni < 2; ++ni)
; #pragma unroll
;       for (int i = 0; i < 16; ++i) acc[mi][ni][i] = 0.f;
;   auto gload = [&](int kt) {
;     ASrc s = asrc(kt);
;     const unsigned voffA = (unsigned)(srow * (int)s.ld * 2 + skc * 16);
;     const char* ua = (const char*)s.p + (long)m0 * s.ld * 2;
; #pragma unroll
;     for (int i = 0; i < 8; ++i) ra[i] = *(const u32x4*)(ua + (long)(32 * i) * s.ld * 2 + voffA);
;     const char* ub = (const char*)Bw + (long)kt * 128;
; #pragma unroll
;     for (int i = 0; i < 4; ++i) rb[i] = *(const u32x4*)(ub + (long)(32 * i) * ldb * 2 + voffB);
;   };
;   auto sstore = [&]() {
; #pragma unroll
;     for (int i = 0; i < 8; ++i) *(u32x4*)(sA + lds_st + i * (32 * 144)) = ra[i];
; #pragma unroll
;     for (int i = 0; i < 4; ++i) *(u32x4*)(sB + lds_st + i * (32 * 144)) = rb[i];
;   };
;   const int nkt = K >> 6;
;   const char* pA = sA + (wm * 128 + lr) * 144 + lh * 16;
;   const char* pB = sB + (wn * 64 + lr) * 144 + lh * 16;
;   gload(0);
;   sstore();
;   __syncthreads();
;   for (int kt = 0; kt < nkt; ++kt) {
;     if (kt + 1 < nkt) gload(kt + 1);
;     __builtin_amdgcn_sched_barrier(0);
;     {
;       bf16x8 ar[3], br[2][2];
;       ar[0] = *(const bf16x8*)(pA);
;       ar[1] = *(const bf16x8*)(pA + 32 * 144);
	ds_write_b128 v134, v[44:47] offset:50688
	v_mov_b32_e32 v0, 0
	v_mov_b32_e32 v1, v0
	v_mov_b32_e32 v2, v0
	v_mov_b32_e32 v3, v0
	v_mov_b32_e32 v4, v0
	v_mov_b32_e32 v5, v0
	v_mov_b32_e32 v6, v0
	v_mov_b32_e32 v7, v0
	v_mov_b32_e32 v8, v0
	v_mov_b32_e32 v9, v0
	v_mov_b32_e32 v10, v0
	v_mov_b32_e32 v11, v0
	v_mov_b32_e32 v12, v0
	v_mov_b32_e32 v13, v0
	v_mov_b32_e32 v14, v0
	v_mov_b32_e32 v15, v0
	v_mov_b32_e32 v16, v0
	v_mov_b32_e32 v17, v0
	v_mov_b32_e32 v18, v0
	v_mov_b32_e32 v19, v0
	v_mov_b32_e32 v20, v0
	v_mov_b32_e32 v21, v0
	v_mov_b32_e32 v22, v0
	v_mov_b32_e32 v23, v0
	v_mov_b32_e32 v24, v0
	v_mov_b32_e32 v25, v0
	v_mov_b32_e32 v26, v0
	v_mov_b32_e32 v27, v0
	v_mov_b32_e32 v28, v0
	v_mov_b32_e32 v29, v0
	v_mov_b32_e32 v30, v0
	v_mov_b32_e32 v31, v0
	v_mov_b32_e32 v32, v0
	v_mov_b32_e32 v33, v0
	v_mov_b32_e32 v34, v0
	v_mov_b32_e32 v35, v0
	v_mov_b32_e32 v36, v0
	v_mov_b32_e32 v37, v0
	v_mov_b32_e32 v38, v0
	v_mov_b32_e32 v39, v0
	v_mov_b32_e32 v40, v0
	v_mov_b32_e32 v41, v0
	v_mov_b32_e32 v42, v0
	v_mov_b32_e32 v43, v0
	v_mov_b32_e32 v44, v0
	v_mov_b32_e32 v45, v0
	v_mov_b32_e32 v46, v0
	v_mov_b32_e32 v47, v0
	v_mov_b32_e32 v48, v0
	v_mov_b32_e32 v49, v0
	v_mov_b32_e32 v50, v0
	v_mov_b32_e32 v51, v0
	v_mov_b32_e32 v52, v0
	v_mov_b32_e32 v53, v0
	v_mov_b32_e32 v54, v0
	v_mov_b32_e32 v55, v0
	v_mov_b32_e32 v56, v0
	v_mov_b32_e32 v57, v0
	v_mov_b32_e32 v58, v0
	v_mov_b32_e32 v59, v0
	v_mov_b32_e32 v60, v0
	v_mov_b32_e32 v61, v0
	v_mov_b32_e32 v62, v0
	v_mov_b32_e32 v63, v0
	v_mov_b32_e32 v64, v0
	v_mov_b32_e32 v65, v0
	v_mov_b32_e32 v66, v0
	v_mov_b32_e32 v67, v0
	v_mov_b32_e32 v68, v0
	v_mov_b32_e32 v69, v0
	v_mov_b32_e32 v70, v0
	v_mov_b32_e32 v71, v0
	v_mov_b32_e32 v72, v0
	v_mov_b32_e32 v73, v0
	v_mov_b32_e32 v74, v0
	v_mov_b32_e32 v75, v0
	v_mov_b32_e32 v76, v0
	v_mov_b32_e32 v77, v0
	v_mov_b32_e32 v78, v0
	v_mov_b32_e32 v79, v0
	v_mov_b32_e32 v80, v0
	v_mov_b32_e32 v81, v0
	v_mov_b32_e32 v82, v0
	v_mov_b32_e32 v83, v0
	v_mov_b32_e32 v84, v0
	v_mov_b32_e32 v85, v0
	v_mov_b32_e32 v86, v0
	v_mov_b32_e32 v87, v0
	v_mov_b32_e32 v88, v0
	v_mov_b32_e32 v89, v0
	v_mov_b32_e32 v90, v0
	v_mov_b32_e32 v91, v0
	v_mov_b32_e32 v92, v0
	v_mov_b32_e32 v93, v0
	v_mov_b32_e32 v94, v0
	v_mov_b32_e32 v95, v0
	v_mov_b32_e32 v96, v0
	v_mov_b32_e32 v97, v0
	v_mov_b32_e32 v98, v0
	v_mov_b32_e32 v99, v0
	v_mov_b32_e32 v100, v0
	v_mov_b32_e32 v101, v0
	v_mov_b32_e32 v102, v0
	v_mov_b32_e32 v103, v0
	v_mov_b32_e32 v104, v0
	v_mov_b32_e32 v105, v0
	v_mov_b32_e32 v106, v0
	v_mov_b32_e32 v107, v0
	v_mov_b32_e32 v108, v0
	v_mov_b32_e32 v109, v0
	v_mov_b32_e32 v110, v0
	v_mov_b32_e32 v111, v0
	v_mov_b32_e32 v112, v0
	v_mov_b32_e32 v113, v0
	v_mov_b32_e32 v114, v0
	v_mov_b32_e32 v115, v0
	v_mov_b32_e32 v116, v0
	v_mov_b32_e32 v117, v0
	v_mov_b32_e32 v118, v0
	v_mov_b32_e32 v119, v0
	v_mov_b32_e32 v120, v0
	v_mov_b32_e32 v121, v0
	v_mov_b32_e32 v122, v0
	v_mov_b32_e32 v123, v0
	v_mov_b32_e32 v124, v0
	v_mov_b32_e32 v125, v0
	v_mov_b32_e32 v126, v0
	v_mov_b32_e32 v127, v0
	v_readlane_b32 s16, v254, 36
	v_readlane_b32 s17, v254, 37
	s_nop 0
	s_load_dwordx2 s[54:55], s[16:17], 0x50
	s_waitcnt lgkmcnt(0)
	s_barrier
	v_readfirstlane_b32 s52, v136
	v_readfirstlane_b32 s53, v137
	s_nop 1
	v_subrev_u32_e32 v245, s52, v136
	s_add_u32 s52, s52, 0x80
	s_addc_u32 s53, s53, 0
	v_add_u32_e32 v246, s75, v245
	v_add_u32_e32 v247, 0x40000, v245
	v_add_u32_e32 v248, 0x60000, v245
	ds_read_b128 v[190:193], v135 offset:36864
	ds_read_b128 v[194:197], v135 offset:41472
	ds_read_b128 v[202:205], v133
	ds_read_b128 v[206:209], v133 offset:4608
	ds_read_b128 v[218:221], v133 offset:9216
	s_branch .LBB0_965
; #define MFMA(a, b, c) __builtin_amdgcn_mfma_f32_32x32x16_bf16((a), (b), (c), 0, 0, 0)
; template <bool SWAP, bool SSQ, class AF>
; DI void gemm_main(AF asrc, int m0, const u16* __restrict__ Bw, int ldb, int K, char* smem,
;                   f32x16 (&acc)[4][2], float ssq_eps, float (&rs)[4]) {
;     ...
;   for (int kt = 0; kt < nkt; ++kt) {
;     if (kt + 1 < nkt) gload(kt + 1);
;     __builtin_amdgcn_sched_barrier(0);
;     {
;       bf16x8 ar[3], br[2][2];
;       ar[0] = *(const bf16x8*)(pA);
;       ar[1] = *(const bf16x8*)(pA + 32 * 144);
;       br[0][0] = *(const bf16x8*)(pB);
;       br[0][1] = *(const bf16x8*)(pB + 32 * 144);
;       __builtin_amdgcn_sched_group_barrier(0x100, 4, 0);
; #pragma unroll
;       for (int t = 0; t < 16; ++t) {
;         const int ks = t >> 2, mi = t & 3;
;         if (t + 2 < 16) {
;           ar[(t + 2) % 3] = *(const bf16x8*)(pA + ((t + 2) & 3) * (32 * 144) + ((t + 2) >> 2) * 32);
;           if (mi == 1 && ks + 1 < 4) {
;             br[(ks + 1) & 1][0] = *(const bf16x8*)(pB + (ks + 1) * 32);
;             br[(ks + 1) & 1][1] = *(const bf16x8*)(pB + 32 * 144 + (ks + 1) * 32);
;             __builtin_amdgcn_sched_group_barrier(0x100, 3, 0);
;           } else {
;             __builtin_amdgcn_sched_group_barrier(0x100, 1, 0);
;           }
;         }
;         acc[mi][0] = SWAP ? MFMA(br[ks & 1][0], ar[t % 3], acc[mi][0]) : MFMA(ar[t % 3], br[ks & 1][0], acc[mi][0]);
;         acc[mi][1] = SWAP ? MFMA(br[ks & 1][1], ar[t % 3], acc[mi][1]) : MFMA(ar[t % 3], br[ks & 1][1], acc[mi][1]);
;         __builtin_amdgcn_sched_group_barrier(0x008, 2, 0);
;         if (SSQ) {
;           u32x4 u = __builtin_bit_cast(u32x4, ar[t % 3]);
; #pragma unroll
;           for (int j = 0; j < 4; ++j) rs[mi] = dot2bf(u[j], rs[mi]);
;         }
;       }
;     }
;     __syncthreads();
;     if (kt + 1 < nkt) sstore();
;     __syncthreads();
;   }
; DI void phase_outproj(const Params& p, const GroupP& g, int l, char* smem, int vb) {
;     ...
;         [&](int kt) {
;           int k0 = kt * 64;
;           if (k0 < 512) return ASrc{uf + k0, 512};
;           if (k0 < 1536) { int kk = k0 - 512; return ASrc{q + (kk >> 7) * 192 + (kk & 127), 1536}; }
;           return ASrc{qd + (k0 - 1536), 512};
;         },
.LBB0_964:
	s_mul_i32 s24, s10, s23
	s_mul_hi_u32 s25, s10, s22
	s_add_i32 s24, s25, s24
	s_mul_i32 s25, s11, s22
	s_add_i32 s24, s24, s25
	s_mul_i32 s25, s10, s22
	v_mul_lo_u32 v140, v139, s22
	s_add_u32 s14, s14, s25
	v_or_b32_e32 v184, v140, v132
	s_addc_u32 s15, s15, s24
	s_lshl_b64 s[50:51], s[22:23], 6
	s_lshl_b64 s[48:49], s[22:23], 8
	v_add_u32_e32 v242, s50, v184
	s_add_u32 s48, s14, s48
	v_add_u32_e32 v243, s50, v242
	s_addc_u32 s49, s15, s49
	v_add_u32_e32 v244, s50, v243
	ds_read_b128 v[222:225], v133 offset:13824
	global_load_dwordx4 v[140:143], v184, s[14:15]
	global_load_dwordx4 v[144:147], v242, s[14:15]
	s_waitcnt lgkmcnt(3)
	v_mfma_f32_32x32x16_bf16 v[112:127], v[190:193], v[202:205], v[112:127]
	v_mfma_f32_32x32x16_bf16 v[96:111], v[194:197], v[202:205], v[96:111]
	ds_read_b128 v[202:205], v135 offset:36896
	ds_read_b128 v[226:229], v135 offset:41504
	global_load_dwordx4 v[148:151], v243, s[14:15]
	global_load_dwordx4 v[152:155], v244, s[14:15]
	s_waitcnt lgkmcnt(4)
	v_mfma_f32_32x32x16_bf16 v[80:95], v[190:193], v[206:209], v[80:95]
	v_mfma_f32_32x32x16_bf16 v[64:79], v[194:197], v[206:209], v[64:79]
	ds_read_b128 v[206:209], v133 offset:32
	global_load_dwordx4 v[156:159], v184, s[48:49]
	global_load_dwordx4 v[160:163], v242, s[48:49]
	s_waitcnt lgkmcnt(4)
	v_mfma_f32_32x32x16_bf16 v[48:63], v[190:193], v[218:221], v[48:63]
	v_mfma_f32_32x32x16_bf16 v[32:47], v[194:197], v[218:221], v[32:47]
	ds_read_b128 v[218:221], v133 offset:4640
	global_load_dwordx4 v[164:167], v243, s[48:49]
	global_load_dwordx4 v[168:171], v244, s[48:49]
	s_waitcnt lgkmcnt(4)
	v_mfma_f32_32x32x16_bf16 v[16:31], v[190:193], v[222:225], v[16:31]
	v_mfma_f32_32x32x16_bf16 v[0:15], v[194:197], v[222:225], v[0:15]
	ds_read_b128 v[190:193], v133 offset:9248
	ds_read_b128 v[194:197], v133 offset:13856
	global_load_dwordx4 v[172:175], v245, s[52:53]
	global_load_dwordx4 v[176:179], v246, s[52:53]
	s_waitcnt lgkmcnt(3)
	v_mfma_f32_32x32x16_bf16 v[112:127], v[202:205], v[206:209], v[112:127]
	v_mfma_f32_32x32x16_bf16 v[96:111], v[226:229], v[206:209], v[96:111]
	ds_read_b128 v[206:209], v135 offset:36928
	ds_read_b128 v[230:233], v135 offset:41536
	global_load_dwordx4 v[180:183], v247, s[52:53]
	global_load_dwordx4 v[186:189], v248, s[52:53]
	s_waitcnt lgkmcnt(4)
	v_mfma_f32_32x32x16_bf16 v[80:95], v[202:205], v[218:221], v[80:95]
	v_mfma_f32_32x32x16_bf16 v[64:79], v[226:229], v[218:221], v[64:79]
	ds_read_b128 v[218:221], v133 offset:64
	ds_read_b128 v[234:237], v133 offset:4672
	s_waitcnt lgkmcnt(5)
	v_mfma_f32_32x32x16_bf16 v[48:63], v[202:205], v[190:193], v[48:63]
	v_mfma_f32_32x32x16_bf16 v[32:47], v[226:229], v[190:193], v[32:47]
	ds_read_b128 v[190:193], v133 offset:9280
	s_waitcnt lgkmcnt(5)
	v_mfma_f32_32x32x16_bf16 v[16:31], v[202:205], v[194:197], v[16:31]
	v_mfma_f32_32x32x16_bf16 v[0:15], v[226:229], v[194:197], v[0:15]
	ds_read_b128 v[202:205], v133 offset:13888
	ds_read_b128 v[238:241], v135 offset:36960
	ds_read_b128 v[222:225], v135 offset:41568
	s_waitcnt lgkmcnt(5)
	v_mfma_f32_32x32x16_bf16 v[112:127], v[206:209], v[218:221], v[112:127]
	v_mfma_f32_32x32x16_bf16 v[96:111], v[230:233], v[218:221], v[96:111]
	ds_read_b128 v[194:197], v133 offset:96
	ds_read_b128 v[218:221], v133 offset:4704
	s_waitcnt lgkmcnt(6)
	v_mfma_f32_32x32x16_bf16 v[80:95], v[206:209], v[234:237], v[80:95]
	v_mfma_f32_32x32x16_bf16 v[64:79], v[230:233], v[234:237], v[64:79]
	ds_read_b128 v[226:229], v133 offset:9312
	ds_read_b128 v[234:237], v133 offset:13920
	s_waitcnt lgkmcnt(0)
	s_barrier
	v_mfma_f32_32x32x16_bf16 v[48:63], v[206:209], v[190:193], v[48:63]
	v_mfma_f32_32x32x16_bf16 v[32:47], v[230:233], v[190:193], v[32:47]
	s_waitcnt vmcnt(11)
	ds_write_b128 v134, v[140:143]
	s_waitcnt vmcnt(10)
	ds_write_b128 v134, v[144:147] offset:4608
	s_waitcnt vmcnt(9)
	ds_write_b128 v134, v[148:151] offset:9216
	s_waitcnt vmcnt(8)
	ds_write_b128 v134, v[152:155] offset:13824
	v_mfma_f32_32x32x16_bf16 v[16:31], v[206:209], v[202:205], v[16:31]
	v_mfma_f32_32x32x16_bf16 v[0:15], v[230:233], v[202:205], v[0:15]
	s_waitcnt vmcnt(7)
	ds_write_b128 v134, v[156:159] offset:18432
	s_waitcnt vmcnt(6)
	ds_write_b128 v134, v[160:163] offset:23040
	s_waitcnt vmcnt(5)
	ds_write_b128 v134, v[164:167] offset:27648
	s_waitcnt vmcnt(4)
	ds_write_b128 v134, v[168:171] offset:32256
	v_mfma_f32_32x32x16_bf16 v[112:127], v[238:241], v[194:197], v[112:127]
	v_mfma_f32_32x32x16_bf16 v[96:111], v[222:225], v[194:197], v[96:111]
	s_waitcnt vmcnt(3)
	ds_write_b128 v134, v[172:175] offset:36864
	s_waitcnt vmcnt(2)
	ds_write_b128 v134, v[176:179] offset:41472
	s_waitcnt vmcnt(1)
	ds_write_b128 v134, v[180:183] offset:46080
	s_waitcnt vmcnt(0)
	ds_write_b128 v134, v[186:189] offset:50688
	v_mfma_f32_32x32x16_bf16 v[80:95], v[238:241], v[218:221], v[80:95]
	v_mfma_f32_32x32x16_bf16 v[64:79], v[222:225], v[218:221], v[64:79]
	s_waitcnt lgkmcnt(0)
	s_barrier
	ds_read_b128 v[190:193], v135 offset:36864
	ds_read_b128 v[194:197], v135 offset:41472
	ds_read_b128 v[202:205], v133
	ds_read_b128 v[206:209], v133 offset:4608
	ds_read_b128 v[218:221], v133 offset:9216
	v_mfma_f32_32x32x16_bf16 v[48:63], v[238:241], v[226:229], v[48:63]
	v_mfma_f32_32x32x16_bf16 v[32:47], v[222:225], v[226:229], v[32:47]
	v_mfma_f32_32x32x16_bf16 v[16:31], v[238:241], v[234:237], v[16:31]
	v_mfma_f32_32x32x16_bf16 v[0:15], v[222:225], v[234:237], v[0:15]
	s_add_u32 s52, s52, 0x80
	s_addc_u32 s53, s53, 0
	s_add_u32 s12, s12, 0x80
	s_addc_u32 s13, s13, 0
	s_add_i32 s7, s7, 64
	s_mov_b32 s41, s9
	s_cmpk_lg_i32 s12, 0xf80
	s_cbranch_scc0 .LBB0_973
